# P11 final-norm loop: the four row-chunk loads issued together per row with counted waits (was load; vmcnt(0); compute; store, four times per row)
# baseline (speedup 1.0000x reference)
.LBB0_793:
	s_add_u32 s12, s78, s8
	s_addc_u32 s13, s79, s9
	s_nop 2
	global_load_dword v48, v42, s[12:13]
	v_lshl_add_u64 v[44:45], s[78:79], 0, v[40:41]
	v_add_co_u32_e32 v52, vcc, s11, v44
	v_lshl_add_u64 v[54:55], s[4:5], 0, v[32:33]
	s_nop 0
	v_addc_co_u32_e32 v53, vcc, 0, v45, vcc
	global_load_dwordx4 v[44:47], v[52:53], off
	global_load_dwordx4 v[62:65], v[52:53], off offset:1024
	global_load_dwordx4 v[66:69], v[52:53], off offset:2048
	global_load_dwordx4 v[70:73], v[52:53], off offset:3072
	s_add_i32 s80, s80, s82
	s_add_u32 s8, s8, s0
	s_addc_u32 s9, s9, s1
	v_lshl_add_u64 v[40:41], v[40:41], 0, s[2:3]
	s_waitcnt vmcnt(4)
	v_fmamk_f32 v56, v48, 0x3a000000, v43
	v_mul_f32_e32 v57, 0x4b800000, v56
	v_cmp_gt_f32_e32 vcc, s10, v56
	s_waitcnt vmcnt(3)
	v_lshlrev_b32_e32 v48, 16, v44
	v_cndmask_b32_e32 v56, v56, v57, vcc
	v_rsq_f32_e32 v56, v56
	v_and_b32_e32 v49, 0xffff0000, v44
	v_lshlrev_b32_e32 v44, 16, v45
	v_and_b32_e32 v45, 0xffff0000, v45
	v_mul_f32_e32 v57, 0x45800000, v56
	v_cndmask_b32_e32 v56, v56, v57, vcc
	v_lshlrev_b32_e32 v50, 16, v46
	v_and_b32_e32 v51, 0xffff0000, v46
	v_lshlrev_b32_e32 v46, 16, v47
	v_and_b32_e32 v47, 0xffff0000, v47
	v_pk_mul_f32 v[48:49], v[56:57], v[48:49] op_sel_hi:[0,1]
	v_pk_mul_f32 v[58:59], v[56:57], v[44:45] op_sel_hi:[0,1]
	v_pk_mul_f32 v[50:51], v[56:57], v[50:51] op_sel_hi:[0,1]
	v_pk_mul_f32 v[60:61], v[56:57], v[46:47] op_sel_hi:[0,1]
	v_pk_mul_f32 v[44:45], v[0:1], v[48:49]
	v_pk_mul_f32 v[46:47], v[2:3], v[58:59]
	v_pk_mul_f32 v[48:49], v[4:5], v[50:51]
	v_pk_mul_f32 v[50:51], v[6:7], v[60:61]
	global_store_dwordx4 v[54:55], v[44:47], off offset:-16 nt
	global_store_dwordx4 v[54:55], v[48:51], off nt
	s_nop 0
	v_lshl_add_u64 v[54:55], s[4:5], 0, v[34:35]
	s_waitcnt vmcnt(4)
	v_mov_b64_e32 v[44:45], v[62:63]
	v_mov_b64_e32 v[46:47], v[64:65]
	v_lshlrev_b32_e32 v48, 16, v44
	v_and_b32_e32 v49, 0xffff0000, v44
	v_lshlrev_b32_e32 v44, 16, v45
	v_and_b32_e32 v45, 0xffff0000, v45
	v_lshlrev_b32_e32 v50, 16, v46
	v_and_b32_e32 v51, 0xffff0000, v46
	v_lshlrev_b32_e32 v46, 16, v47
	v_and_b32_e32 v47, 0xffff0000, v47
	v_pk_mul_f32 v[48:49], v[56:57], v[48:49] op_sel_hi:[0,1]
	v_pk_mul_f32 v[58:59], v[56:57], v[44:45] op_sel_hi:[0,1]
	v_pk_mul_f32 v[50:51], v[56:57], v[50:51] op_sel_hi:[0,1]
	v_pk_mul_f32 v[60:61], v[56:57], v[46:47] op_sel_hi:[0,1]
	v_pk_mul_f32 v[44:45], v[8:9], v[48:49]
	v_pk_mul_f32 v[46:47], v[10:11], v[58:59]
	v_pk_mul_f32 v[48:49], v[12:13], v[50:51]
	v_pk_mul_f32 v[50:51], v[14:15], v[60:61]
	global_store_dwordx4 v[54:55], v[44:47], off offset:-16 nt
	global_store_dwordx4 v[54:55], v[48:51], off nt
	s_nop 0
	v_lshl_add_u64 v[54:55], s[4:5], 0, v[36:37]
	s_waitcnt vmcnt(5)
	v_mov_b64_e32 v[44:45], v[66:67]
	v_mov_b64_e32 v[46:47], v[68:69]
	v_lshlrev_b32_e32 v48, 16, v44
	v_and_b32_e32 v49, 0xffff0000, v44
	v_lshlrev_b32_e32 v44, 16, v45
	v_and_b32_e32 v45, 0xffff0000, v45
	v_lshlrev_b32_e32 v50, 16, v46
	v_and_b32_e32 v51, 0xffff0000, v46
	v_lshlrev_b32_e32 v46, 16, v47
	v_and_b32_e32 v47, 0xffff0000, v47
	v_pk_mul_f32 v[48:49], v[56:57], v[48:49] op_sel_hi:[0,1]
	v_pk_mul_f32 v[58:59], v[56:57], v[44:45] op_sel_hi:[0,1]
	v_pk_mul_f32 v[50:51], v[56:57], v[50:51] op_sel_hi:[0,1]
	v_pk_mul_f32 v[60:61], v[56:57], v[46:47] op_sel_hi:[0,1]
	v_pk_mul_f32 v[44:45], v[16:17], v[48:49]
	v_pk_mul_f32 v[46:47], v[18:19], v[58:59]
	v_pk_mul_f32 v[48:49], v[20:21], v[50:51]
	v_pk_mul_f32 v[50:51], v[22:23], v[60:61]
	global_store_dwordx4 v[54:55], v[44:47], off nt
	global_store_dwordx4 v[54:55], v[48:51], off offset:16 nt
	s_nop 0
	v_lshl_add_u64 v[52:53], s[4:5], 0, v[38:39]
	s_add_u32 s4, s4, s6
	s_addc_u32 s5, s5, s7
	s_cmpk_gt_i32 s80, 0x7fff
	s_waitcnt vmcnt(6)
	v_mov_b64_e32 v[44:45], v[70:71]
	v_mov_b64_e32 v[46:47], v[72:73]
	v_lshlrev_b32_e32 v48, 16, v44
	v_and_b32_e32 v49, 0xffff0000, v44
	v_lshlrev_b32_e32 v44, 16, v45
	v_and_b32_e32 v45, 0xffff0000, v45
	v_lshlrev_b32_e32 v50, 16, v46
	v_and_b32_e32 v51, 0xffff0000, v46
	v_lshlrev_b32_e32 v46, 16, v47
	v_and_b32_e32 v47, 0xffff0000, v47
	v_pk_mul_f32 v[48:49], v[56:57], v[48:49] op_sel_hi:[0,1]
	v_pk_mul_f32 v[54:55], v[56:57], v[44:45] op_sel_hi:[0,1]
	v_pk_mul_f32 v[50:51], v[56:57], v[50:51] op_sel_hi:[0,1]
	v_pk_mul_f32 v[56:57], v[56:57], v[46:47] op_sel_hi:[0,1]
	v_pk_mul_f32 v[44:45], v[24:25], v[48:49]
	v_pk_mul_f32 v[46:47], v[26:27], v[54:55]
	v_pk_mul_f32 v[48:49], v[28:29], v[50:51]
	v_pk_mul_f32 v[50:51], v[30:31], v[56:57]
	global_store_dwordx4 v[52:53], v[44:47], off nt
	global_store_dwordx4 v[52:53], v[48:51], off offset:16 nt
	s_cbranch_scc0 .LBB0_793
